# strategy 7: swiglu epilogue store addresses by constant increments instead of a 64-bit multiply-add per row block; dead address arithmetic removed
# speedup vs baseline: 1.0004x; 1.0004x over previous
.LBB0_223:
	s_cmp_lt_i32 s22, 64
	s_cselect_b32 s15, s62, 0x2c00
	s_cmp_gt_i32 s22, 31
	s_cselect_b32 s15, s15, 0
	v_lshl_add_u32 v160, s22, 8, v168
	s_lshl_b32 s15, s15, 2
	s_add_u32 s15, s49, s15
	v_ashrrev_i32_e32 v161, 31, v160
	s_addc_u32 s17, s56, 0
	s_lshl_b32 s24, s64, 8
	v_lshl_add_u64 v[164:165], v[160:161], 2, s[6:7]
	s_ashr_i32 s25, s24, 31
	v_mov_b32_e32 v194, 0xbfb8aa3b
	v_mov_b32_e32 v195, 0xbfb8aa3b
	v_mov_b32_e32 v196, 1.0
	v_mov_b32_e32 v197, 1.0
	v_mov_b32_e32 v198, 0x16000
	v_mov_b32_e32 v199, 0
	v_mov_b32_e32 v200, 0x6e000
	v_mov_b32_e32 v201, 0
	global_load_dword v161, v[164:165], off
	global_load_dword v241, v[164:165], off offset:64
	global_load_dword v242, v[164:165], off offset:128
	global_load_dword v243, v[164:165], off offset:192
	global_load_dword v244, v[164:165], off offset:512
	global_load_dword v245, v[164:165], off offset:576
	global_load_dword v246, v[164:165], off offset:640
	global_load_dword v247, v[164:165], off offset:704
	s_lshl_b64 s[24:25], s[24:25], 2
	s_add_u32 s15, s15, s24
	s_addc_u32 s17, s17, s25
	s_add_u32 s24, s15, s63
	s_addc_u32 s25, s17, 0
	global_load_dwordx4 v[112:115], v174, s[24:25]
	global_load_dwordx4 v[116:119], v174, s[24:25] offset:512
	global_load_dwordx4 v[104:107], v174, s[24:25] offset:16
	global_load_dwordx4 v[108:111], v174, s[24:25] offset:528
	v_or_b32_e32 v180, 16, v160
	v_ashrrev_i32_e32 v181, 31, v180
	v_lshl_or_b32 v166, s64, 7, v170
	v_mov_b64_e32 v[162:163], s[36:37]
	v_ashrrev_i32_e32 v167, 31, v166
	v_mad_i64_i32 v[178:179], s[24:25], v160, s62, v[162:163]
	v_lshlrev_b64 v[166:167], 1, v[166:167]
	v_lshl_add_u64 v[178:179], v[178:179], 0, v[166:167]
	s_andn2_b64 vcc, exec, s[2:3]
	s_mov_b64 s[2:3], -1
	s_waitcnt vmcnt(0)
	v_fmamk_f32 v161, v161, 0x3a800000, v175
	v_rsq_f32_e32 v182, v161
	s_nop 0
	v_pk_fma_f32 v[140:141], v[140:141], v[182:183], v[112:113] op_sel_hi:[1,0,1]
	v_pk_fma_f32 v[142:143], v[142:143], v[182:183], v[114:115] op_sel_hi:[1,0,1]
	v_pk_fma_f32 v[136:137], v[136:137], v[182:183], v[104:105] op_sel_hi:[1,0,1]
	v_pk_fma_f32 v[138:139], v[138:139], v[182:183], v[106:107] op_sel_hi:[1,0,1]
	v_pk_fma_f32 v[132:133], v[132:133], v[182:183], v[116:117] op_sel_hi:[1,0,1]
	v_pk_fma_f32 v[134:135], v[134:135], v[182:183], v[118:119] op_sel_hi:[1,0,1]
	v_pk_fma_f32 v[128:129], v[128:129], v[182:183], v[108:109] op_sel_hi:[1,0,1]
	v_pk_fma_f32 v[130:131], v[130:131], v[182:183], v[110:111] op_sel_hi:[1,0,1]
	v_pk_mul_f32 v[182:183], v[140:141], v[194:195]
	v_pk_mul_f32 v[186:187], v[142:143], v[194:195]
	v_pk_mul_f32 v[188:189], v[136:137], v[194:195]
	v_pk_mul_f32 v[190:191], v[138:139], v[194:195]
	v_exp_f32_e32 v182, v182
	v_exp_f32_e32 v183, v183
	v_exp_f32_e32 v186, v186
	v_exp_f32_e32 v187, v187
	v_exp_f32_e32 v188, v188
	v_exp_f32_e32 v189, v189
	v_exp_f32_e32 v190, v190
	v_exp_f32_e32 v191, v191
	v_pk_add_f32 v[182:183], v[182:183], v[196:197]
	v_pk_add_f32 v[186:187], v[186:187], v[196:197]
	v_pk_add_f32 v[188:189], v[188:189], v[196:197]
	v_pk_add_f32 v[190:191], v[190:191], v[196:197]
	v_rcp_f32_e32 v182, v182
	v_rcp_f32_e32 v183, v183
	v_rcp_f32_e32 v186, v186
	v_rcp_f32_e32 v187, v187
	v_rcp_f32_e32 v188, v188
	v_rcp_f32_e32 v189, v189
	v_rcp_f32_e32 v190, v190
	v_rcp_f32_e32 v191, v191
	v_pk_mul_f32 v[140:141], v[140:141], v[182:183]
	v_pk_mul_f32 v[142:143], v[142:143], v[186:187]
	v_pk_mul_f32 v[136:137], v[136:137], v[188:189]
	v_pk_mul_f32 v[138:139], v[138:139], v[190:191]
	v_pk_mul_f32 v[132:133], v[132:133], v[140:141]
	v_pk_mul_f32 v[134:135], v[134:135], v[142:143]
	v_pk_mul_f32 v[136:137], v[128:129], v[136:137]
	v_pk_mul_f32 v[138:139], v[130:131], v[138:139]
	v_cvt_pk_f16_f32 v128, v132, v133
	v_cvt_pk_f16_f32 v129, v134, v135
	v_cvt_pk_f16_f32 v130, v136, v137
	v_cvt_pk_f16_f32 v131, v138, v139
	global_store_dwordx4 v[178:179], v[128:131], off
	s_nop 0
	s_nop 0
	v_or_b32_e32 v128, 32, v160
	v_lshl_add_u64 v[130:131], v[178:179], 0, v[198:199]
	v_fmamk_f32 v129, v241, 0x3a800000, v175
	v_rsq_f32_e32 v132, v129
	v_ashrrev_i32_e32 v129, 31, v128
	v_pk_fma_f32 v[124:125], v[124:125], v[132:133], v[112:113] op_sel_hi:[1,0,1]
	v_pk_fma_f32 v[126:127], v[126:127], v[132:133], v[114:115] op_sel_hi:[1,0,1]
	v_pk_fma_f32 v[120:121], v[120:121], v[132:133], v[104:105] op_sel_hi:[1,0,1]
	v_pk_fma_f32 v[122:123], v[122:123], v[132:133], v[106:107] op_sel_hi:[1,0,1]
	v_pk_fma_f32 v[100:101], v[100:101], v[132:133], v[116:117] op_sel_hi:[1,0,1]
	v_pk_fma_f32 v[102:103], v[102:103], v[132:133], v[118:119] op_sel_hi:[1,0,1]
	v_pk_fma_f32 v[96:97], v[96:97], v[132:133], v[108:109] op_sel_hi:[1,0,1]
	v_pk_fma_f32 v[98:99], v[98:99], v[132:133], v[110:111] op_sel_hi:[1,0,1]
	v_pk_mul_f32 v[132:133], v[124:125], v[194:195]
	v_pk_mul_f32 v[136:137], v[126:127], v[194:195]
	v_pk_mul_f32 v[138:139], v[120:121], v[194:195]
	v_pk_mul_f32 v[140:141], v[122:123], v[194:195]
	v_exp_f32_e32 v132, v132
	v_exp_f32_e32 v133, v133
	v_exp_f32_e32 v136, v136
	v_exp_f32_e32 v137, v137
	v_exp_f32_e32 v138, v138
	v_exp_f32_e32 v139, v139
	v_exp_f32_e32 v140, v140
	v_exp_f32_e32 v141, v141
	v_pk_add_f32 v[132:133], v[132:133], v[196:197]
	v_pk_add_f32 v[136:137], v[136:137], v[196:197]
	v_pk_add_f32 v[138:139], v[138:139], v[196:197]
	v_pk_add_f32 v[140:141], v[140:141], v[196:197]
	v_rcp_f32_e32 v132, v132
	v_rcp_f32_e32 v133, v133
	v_rcp_f32_e32 v136, v136
	v_rcp_f32_e32 v137, v137
	v_rcp_f32_e32 v138, v138
	v_rcp_f32_e32 v139, v139
	v_rcp_f32_e32 v140, v140
	v_rcp_f32_e32 v141, v141
	v_pk_mul_f32 v[124:125], v[124:125], v[132:133]
	v_pk_mul_f32 v[126:127], v[126:127], v[136:137]
	v_pk_mul_f32 v[120:121], v[120:121], v[138:139]
	v_pk_mul_f32 v[122:123], v[122:123], v[140:141]
	v_pk_mul_f32 v[100:101], v[100:101], v[124:125]
	v_pk_mul_f32 v[102:103], v[102:103], v[126:127]
	v_pk_mul_f32 v[120:121], v[96:97], v[120:121]
	v_pk_mul_f32 v[122:123], v[98:99], v[122:123]
	v_cvt_pk_f16_f32 v96, v100, v101
	v_cvt_pk_f16_f32 v97, v102, v103
	v_cvt_pk_f16_f32 v98, v120, v121
	v_cvt_pk_f16_f32 v99, v122, v123
	global_store_dwordx4 v[130:131], v[96:99], off
	s_nop 0
	s_nop 0
	v_or_b32_e32 v96, 48, v160
	v_lshl_add_u64 v[98:99], v[130:131], 0, v[198:199]
	v_fmamk_f32 v97, v242, 0x3a800000, v175
	v_rsq_f32_e32 v100, v97
	v_ashrrev_i32_e32 v97, 31, v96
	v_pk_fma_f32 v[92:93], v[92:93], v[100:101], v[112:113] op_sel_hi:[1,0,1]
	v_pk_fma_f32 v[94:95], v[94:95], v[100:101], v[114:115] op_sel_hi:[1,0,1]
	v_pk_fma_f32 v[88:89], v[88:89], v[100:101], v[104:105] op_sel_hi:[1,0,1]
	v_pk_fma_f32 v[90:91], v[90:91], v[100:101], v[106:107] op_sel_hi:[1,0,1]
	v_pk_fma_f32 v[84:85], v[84:85], v[100:101], v[116:117] op_sel_hi:[1,0,1]
	v_pk_fma_f32 v[86:87], v[86:87], v[100:101], v[118:119] op_sel_hi:[1,0,1]
	v_pk_fma_f32 v[80:81], v[80:81], v[100:101], v[108:109] op_sel_hi:[1,0,1]
	v_pk_fma_f32 v[82:83], v[82:83], v[100:101], v[110:111] op_sel_hi:[1,0,1]
	v_pk_mul_f32 v[100:101], v[92:93], v[194:195]
	v_pk_mul_f32 v[120:121], v[94:95], v[194:195]
	v_pk_mul_f32 v[122:123], v[88:89], v[194:195]
	v_pk_mul_f32 v[124:125], v[90:91], v[194:195]
	v_exp_f32_e32 v100, v100
	v_exp_f32_e32 v101, v101
	v_exp_f32_e32 v120, v120
	v_exp_f32_e32 v121, v121
	v_exp_f32_e32 v122, v122
	v_exp_f32_e32 v123, v123
	v_exp_f32_e32 v124, v124
	v_exp_f32_e32 v125, v125
	v_pk_add_f32 v[100:101], v[100:101], v[196:197]
	v_pk_add_f32 v[120:121], v[120:121], v[196:197]
	v_pk_add_f32 v[122:123], v[122:123], v[196:197]
	v_pk_add_f32 v[124:125], v[124:125], v[196:197]
	v_rcp_f32_e32 v100, v100
	v_rcp_f32_e32 v101, v101
	v_rcp_f32_e32 v120, v120
	v_rcp_f32_e32 v121, v121
	v_rcp_f32_e32 v122, v122
	v_rcp_f32_e32 v123, v123
	v_rcp_f32_e32 v124, v124
	v_rcp_f32_e32 v125, v125
	v_pk_mul_f32 v[92:93], v[92:93], v[100:101]
	v_pk_mul_f32 v[94:95], v[94:95], v[120:121]
	v_pk_mul_f32 v[88:89], v[88:89], v[122:123]
	v_pk_mul_f32 v[90:91], v[90:91], v[124:125]
	v_pk_mul_f32 v[84:85], v[84:85], v[92:93]
	v_pk_mul_f32 v[86:87], v[86:87], v[94:95]
	v_pk_mul_f32 v[88:89], v[80:81], v[88:89]
	v_pk_mul_f32 v[90:91], v[82:83], v[90:91]
	v_cvt_pk_f16_f32 v80, v84, v85
	v_cvt_pk_f16_f32 v81, v86, v87
	v_cvt_pk_f16_f32 v82, v88, v89
	v_cvt_pk_f16_f32 v83, v90, v91
	global_store_dwordx4 v[98:99], v[80:83], off
	s_nop 0
	s_nop 0
	v_lshl_add_u64 v[82:83], v[98:99], 0, v[198:199]
	v_fmamk_f32 v80, v243, 0x3a800000, v175
	v_rsq_f32_e32 v80, v80
	s_nop 0
	v_pk_fma_f32 v[76:77], v[76:77], v[80:81], v[112:113] op_sel_hi:[1,0,1]
	v_pk_fma_f32 v[78:79], v[78:79], v[80:81], v[114:115] op_sel_hi:[1,0,1]
	v_pk_fma_f32 v[72:73], v[72:73], v[80:81], v[104:105] op_sel_hi:[1,0,1]
	v_pk_fma_f32 v[74:75], v[74:75], v[80:81], v[106:107] op_sel_hi:[1,0,1]
	v_pk_fma_f32 v[68:69], v[68:69], v[80:81], v[116:117] op_sel_hi:[1,0,1]
	v_pk_fma_f32 v[70:71], v[70:71], v[80:81], v[118:119] op_sel_hi:[1,0,1]
	v_pk_fma_f32 v[64:65], v[64:65], v[80:81], v[108:109] op_sel_hi:[1,0,1]
	v_pk_fma_f32 v[66:67], v[66:67], v[80:81], v[110:111] op_sel_hi:[1,0,1]
	v_pk_mul_f32 v[80:81], v[76:77], v[194:195]
	v_pk_mul_f32 v[84:85], v[78:79], v[194:195]
	v_pk_mul_f32 v[86:87], v[72:73], v[194:195]
	v_pk_mul_f32 v[88:89], v[74:75], v[194:195]
	v_exp_f32_e32 v80, v80
	v_exp_f32_e32 v81, v81
	v_exp_f32_e32 v84, v84
	v_exp_f32_e32 v85, v85
	v_exp_f32_e32 v86, v86
	v_exp_f32_e32 v87, v87
	v_exp_f32_e32 v88, v88
	v_exp_f32_e32 v89, v89
	v_pk_add_f32 v[80:81], v[80:81], v[196:197]
	v_pk_add_f32 v[84:85], v[84:85], v[196:197]
	v_pk_add_f32 v[86:87], v[86:87], v[196:197]
	v_pk_add_f32 v[88:89], v[88:89], v[196:197]
	v_rcp_f32_e32 v80, v80
	v_rcp_f32_e32 v81, v81
	v_rcp_f32_e32 v84, v84
	v_rcp_f32_e32 v85, v85
	v_rcp_f32_e32 v86, v86
	v_rcp_f32_e32 v87, v87
	v_rcp_f32_e32 v88, v88
	v_rcp_f32_e32 v89, v89
	v_pk_mul_f32 v[76:77], v[76:77], v[80:81]
	v_pk_mul_f32 v[78:79], v[78:79], v[84:85]
	v_pk_mul_f32 v[72:73], v[72:73], v[86:87]
	v_pk_mul_f32 v[74:75], v[74:75], v[88:89]
	v_pk_mul_f32 v[68:69], v[68:69], v[76:77]
	v_pk_mul_f32 v[70:71], v[70:71], v[78:79]
	v_pk_mul_f32 v[72:73], v[64:65], v[72:73]
	v_pk_mul_f32 v[74:75], v[66:67], v[74:75]
	v_cvt_pk_f16_f32 v64, v68, v69
	v_cvt_pk_f16_f32 v65, v70, v71
	v_cvt_pk_f16_f32 v66, v72, v73
	v_cvt_pk_f16_f32 v67, v74, v75
	global_store_dwordx4 v[82:83], v[64:67], off
	s_nop 0
	s_nop 0
	v_add_u32_e32 v65, 0x80, v160
	v_lshl_add_u64 v[66:67], v[82:83], 0, v[200:201]
	v_fmamk_f32 v64, v244, 0x3a800000, v175
	v_rsq_f32_e32 v64, v64
	s_nop 0
	v_pk_fma_f32 v[60:61], v[60:61], v[64:65], v[112:113] op_sel_hi:[1,0,1]
	v_pk_fma_f32 v[62:63], v[62:63], v[64:65], v[114:115] op_sel_hi:[1,0,1]
	v_pk_fma_f32 v[56:57], v[56:57], v[64:65], v[104:105] op_sel_hi:[1,0,1]
	v_pk_fma_f32 v[58:59], v[58:59], v[64:65], v[106:107] op_sel_hi:[1,0,1]
	v_pk_fma_f32 v[52:53], v[52:53], v[64:65], v[116:117] op_sel_hi:[1,0,1]
	v_pk_fma_f32 v[54:55], v[54:55], v[64:65], v[118:119] op_sel_hi:[1,0,1]
	v_pk_fma_f32 v[48:49], v[48:49], v[64:65], v[108:109] op_sel_hi:[1,0,1]
	v_pk_fma_f32 v[50:51], v[50:51], v[64:65], v[110:111] op_sel_hi:[1,0,1]
	v_pk_mul_f32 v[64:65], v[60:61], v[194:195]
	v_pk_mul_f32 v[68:69], v[62:63], v[194:195]
	v_pk_mul_f32 v[70:71], v[56:57], v[194:195]
	v_pk_mul_f32 v[72:73], v[58:59], v[194:195]
	v_exp_f32_e32 v64, v64
	v_exp_f32_e32 v65, v65
	v_exp_f32_e32 v68, v68
	v_exp_f32_e32 v69, v69
	v_exp_f32_e32 v70, v70
	v_exp_f32_e32 v71, v71
	v_exp_f32_e32 v72, v72
	v_exp_f32_e32 v73, v73
	v_pk_add_f32 v[64:65], v[64:65], v[196:197]
	v_pk_add_f32 v[68:69], v[68:69], v[196:197]
	v_pk_add_f32 v[70:71], v[70:71], v[196:197]
	v_pk_add_f32 v[72:73], v[72:73], v[196:197]
	v_rcp_f32_e32 v64, v64
	v_rcp_f32_e32 v65, v65
	v_rcp_f32_e32 v68, v68
	v_rcp_f32_e32 v69, v69
	v_rcp_f32_e32 v70, v70
	v_rcp_f32_e32 v71, v71
	v_rcp_f32_e32 v72, v72
	v_rcp_f32_e32 v73, v73
	v_pk_mul_f32 v[60:61], v[60:61], v[64:65]
	v_pk_mul_f32 v[62:63], v[62:63], v[68:69]
	v_pk_mul_f32 v[56:57], v[56:57], v[70:71]
	v_pk_mul_f32 v[58:59], v[58:59], v[72:73]
	v_pk_mul_f32 v[52:53], v[52:53], v[60:61]
	v_pk_mul_f32 v[54:55], v[54:55], v[62:63]
	v_pk_mul_f32 v[56:57], v[48:49], v[56:57]
	v_pk_mul_f32 v[58:59], v[50:51], v[58:59]
	v_cvt_pk_f16_f32 v48, v52, v53
	v_cvt_pk_f16_f32 v49, v54, v55
	v_cvt_pk_f16_f32 v50, v56, v57
	v_cvt_pk_f16_f32 v51, v58, v59
	global_store_dwordx4 v[66:67], v[48:51], off
	s_nop 0
	s_nop 0
	v_add_u32_e32 v49, 0x90, v160
	v_lshl_add_u64 v[50:51], v[66:67], 0, v[198:199]
	v_fmamk_f32 v48, v245, 0x3a800000, v175
	v_rsq_f32_e32 v48, v48
	s_nop 0
	v_pk_fma_f32 v[44:45], v[44:45], v[48:49], v[112:113] op_sel_hi:[1,0,1]
	v_pk_fma_f32 v[46:47], v[46:47], v[48:49], v[114:115] op_sel_hi:[1,0,1]
	v_pk_fma_f32 v[40:41], v[40:41], v[48:49], v[104:105] op_sel_hi:[1,0,1]
	v_pk_fma_f32 v[42:43], v[42:43], v[48:49], v[106:107] op_sel_hi:[1,0,1]
	v_pk_fma_f32 v[36:37], v[36:37], v[48:49], v[116:117] op_sel_hi:[1,0,1]
	v_pk_fma_f32 v[38:39], v[38:39], v[48:49], v[118:119] op_sel_hi:[1,0,1]
	v_pk_fma_f32 v[32:33], v[32:33], v[48:49], v[108:109] op_sel_hi:[1,0,1]
	v_pk_fma_f32 v[34:35], v[34:35], v[48:49], v[110:111] op_sel_hi:[1,0,1]
	v_pk_mul_f32 v[48:49], v[44:45], v[194:195]
	v_pk_mul_f32 v[52:53], v[46:47], v[194:195]
	v_pk_mul_f32 v[54:55], v[40:41], v[194:195]
	v_pk_mul_f32 v[56:57], v[42:43], v[194:195]
	v_exp_f32_e32 v48, v48
	v_exp_f32_e32 v49, v49
	v_exp_f32_e32 v52, v52
	v_exp_f32_e32 v53, v53
	v_exp_f32_e32 v54, v54
	v_exp_f32_e32 v55, v55
	v_exp_f32_e32 v56, v56
	v_exp_f32_e32 v57, v57
	v_pk_add_f32 v[48:49], v[48:49], v[196:197]
	v_pk_add_f32 v[52:53], v[52:53], v[196:197]
	v_pk_add_f32 v[54:55], v[54:55], v[196:197]
	v_pk_add_f32 v[56:57], v[56:57], v[196:197]
	v_rcp_f32_e32 v48, v48
	v_rcp_f32_e32 v49, v49
	v_rcp_f32_e32 v52, v52
	v_rcp_f32_e32 v53, v53
	v_rcp_f32_e32 v54, v54
	v_rcp_f32_e32 v55, v55
	v_rcp_f32_e32 v56, v56
	v_rcp_f32_e32 v57, v57
	v_pk_mul_f32 v[44:45], v[44:45], v[48:49]
	v_pk_mul_f32 v[46:47], v[46:47], v[52:53]
	v_pk_mul_f32 v[40:41], v[40:41], v[54:55]
	v_pk_mul_f32 v[42:43], v[42:43], v[56:57]
	v_pk_mul_f32 v[36:37], v[36:37], v[44:45]
	v_pk_mul_f32 v[38:39], v[38:39], v[46:47]
	v_pk_mul_f32 v[40:41], v[32:33], v[40:41]
	v_pk_mul_f32 v[42:43], v[34:35], v[42:43]
	v_cvt_pk_f16_f32 v32, v36, v37
	v_cvt_pk_f16_f32 v33, v38, v39
	v_cvt_pk_f16_f32 v34, v40, v41
	v_cvt_pk_f16_f32 v35, v42, v43
	global_store_dwordx4 v[50:51], v[32:35], off
	s_nop 0
	s_nop 0
	v_add_u32_e32 v33, 0xa0, v160
	v_lshl_add_u64 v[34:35], v[50:51], 0, v[198:199]
	v_fmamk_f32 v32, v246, 0x3a800000, v175
	v_rsq_f32_e32 v32, v32
	s_nop 0
	v_pk_fma_f32 v[28:29], v[28:29], v[32:33], v[112:113] op_sel_hi:[1,0,1]
	v_pk_fma_f32 v[30:31], v[30:31], v[32:33], v[114:115] op_sel_hi:[1,0,1]
	v_pk_fma_f32 v[24:25], v[24:25], v[32:33], v[104:105] op_sel_hi:[1,0,1]
	v_pk_fma_f32 v[26:27], v[26:27], v[32:33], v[106:107] op_sel_hi:[1,0,1]
	v_pk_fma_f32 v[20:21], v[20:21], v[32:33], v[116:117] op_sel_hi:[1,0,1]
	v_pk_fma_f32 v[22:23], v[22:23], v[32:33], v[118:119] op_sel_hi:[1,0,1]
	v_pk_fma_f32 v[16:17], v[16:17], v[32:33], v[108:109] op_sel_hi:[1,0,1]
	v_pk_fma_f32 v[18:19], v[18:19], v[32:33], v[110:111] op_sel_hi:[1,0,1]
	v_pk_mul_f32 v[32:33], v[28:29], v[194:195]
	v_pk_mul_f32 v[36:37], v[30:31], v[194:195]
	v_pk_mul_f32 v[38:39], v[24:25], v[194:195]
	v_pk_mul_f32 v[40:41], v[26:27], v[194:195]
	v_exp_f32_e32 v32, v32
	v_exp_f32_e32 v33, v33
	v_exp_f32_e32 v36, v36
	v_exp_f32_e32 v37, v37
	v_exp_f32_e32 v38, v38
	v_exp_f32_e32 v39, v39
	v_exp_f32_e32 v40, v40
	v_exp_f32_e32 v41, v41
	v_pk_add_f32 v[32:33], v[32:33], v[196:197]
	v_pk_add_f32 v[36:37], v[36:37], v[196:197]
	v_pk_add_f32 v[38:39], v[38:39], v[196:197]
	v_pk_add_f32 v[40:41], v[40:41], v[196:197]
	v_rcp_f32_e32 v32, v32
	v_rcp_f32_e32 v33, v33
	v_rcp_f32_e32 v36, v36
	v_rcp_f32_e32 v37, v37
	v_rcp_f32_e32 v38, v38
	v_rcp_f32_e32 v39, v39
	v_rcp_f32_e32 v40, v40
	v_rcp_f32_e32 v41, v41
	v_pk_mul_f32 v[28:29], v[28:29], v[32:33]
	v_pk_mul_f32 v[30:31], v[30:31], v[36:37]
	v_pk_mul_f32 v[24:25], v[24:25], v[38:39]
	v_pk_mul_f32 v[26:27], v[26:27], v[40:41]
	v_pk_mul_f32 v[20:21], v[20:21], v[28:29]
	v_pk_mul_f32 v[22:23], v[22:23], v[30:31]
	v_pk_mul_f32 v[24:25], v[16:17], v[24:25]
	v_pk_mul_f32 v[26:27], v[18:19], v[26:27]
	v_cvt_pk_f16_f32 v16, v20, v21
	v_cvt_pk_f16_f32 v17, v22, v23
	v_cvt_pk_f16_f32 v18, v24, v25
	v_cvt_pk_f16_f32 v19, v26, v27
	global_store_dwordx4 v[34:35], v[16:19], off
	s_nop 0
	s_nop 0
	v_add_u32_e32 v17, 0xb0, v160
	v_lshl_add_u64 v[18:19], v[34:35], 0, v[198:199]
	v_fmamk_f32 v16, v247, 0x3a800000, v175
	v_rsq_f32_e32 v16, v16
	s_nop 0
	v_pk_fma_f32 v[12:13], v[12:13], v[16:17], v[112:113] op_sel_hi:[1,0,1]
	v_pk_fma_f32 v[14:15], v[14:15], v[16:17], v[114:115] op_sel_hi:[1,0,1]
	v_pk_fma_f32 v[8:9], v[8:9], v[16:17], v[104:105] op_sel_hi:[1,0,1]
	v_pk_fma_f32 v[10:11], v[10:11], v[16:17], v[106:107] op_sel_hi:[1,0,1]
	v_pk_fma_f32 v[4:5], v[4:5], v[16:17], v[116:117] op_sel_hi:[1,0,1]
	v_pk_fma_f32 v[6:7], v[6:7], v[16:17], v[118:119] op_sel_hi:[1,0,1]
	v_pk_fma_f32 v[0:1], v[0:1], v[16:17], v[108:109] op_sel_hi:[1,0,1]
	v_pk_fma_f32 v[2:3], v[2:3], v[16:17], v[110:111] op_sel_hi:[1,0,1]
	v_pk_mul_f32 v[16:17], v[12:13], v[194:195]
	v_pk_mul_f32 v[20:21], v[14:15], v[194:195]
	v_pk_mul_f32 v[22:23], v[8:9], v[194:195]
	v_pk_mul_f32 v[24:25], v[10:11], v[194:195]
	v_exp_f32_e32 v16, v16
	v_exp_f32_e32 v17, v17
	v_exp_f32_e32 v20, v20
	v_exp_f32_e32 v21, v21
	v_exp_f32_e32 v22, v22
	v_exp_f32_e32 v23, v23
	v_exp_f32_e32 v24, v24
	v_exp_f32_e32 v25, v25
	v_pk_add_f32 v[16:17], v[16:17], v[196:197]
	v_pk_add_f32 v[20:21], v[20:21], v[196:197]
	v_pk_add_f32 v[22:23], v[22:23], v[196:197]
	v_pk_add_f32 v[24:25], v[24:25], v[196:197]
	v_rcp_f32_e32 v16, v16
	v_rcp_f32_e32 v17, v17
	v_rcp_f32_e32 v20, v20
	v_rcp_f32_e32 v21, v21
	v_rcp_f32_e32 v22, v22
	v_rcp_f32_e32 v23, v23
	v_rcp_f32_e32 v24, v24
	v_rcp_f32_e32 v25, v25
	v_pk_mul_f32 v[12:13], v[12:13], v[16:17]
	v_pk_mul_f32 v[14:15], v[14:15], v[20:21]
	v_pk_mul_f32 v[8:9], v[8:9], v[22:23]
	v_pk_mul_f32 v[10:11], v[10:11], v[24:25]
	v_pk_mul_f32 v[4:5], v[4:5], v[12:13]
	v_pk_mul_f32 v[6:7], v[6:7], v[14:15]
	v_pk_mul_f32 v[8:9], v[0:1], v[8:9]
	v_pk_mul_f32 v[10:11], v[2:3], v[10:11]
	v_cvt_pk_f16_f32 v0, v4, v5
	v_cvt_pk_f16_f32 v1, v6, v7
	v_cvt_pk_f16_f32 v2, v8, v9
	v_cvt_pk_f16_f32 v3, v10, v11
	global_store_dwordx4 v[18:19], v[0:3], off
	s_cbranch_vccnz .LBB0_212
	s_andn2_b64 vcc, exec, s[4:5]
	s_cbranch_vccnz .LBB0_211
	s_barrier
	s_branch .LBB0_211

.LBB0_876:
	s_cmp_lt_i32 s22, 64
	s_cselect_b32 s15, s60, 0x2c00
	s_cmp_gt_i32 s22, 31
	s_cselect_b32 s15, s15, 0
	v_lshl_add_u32 v160, s22, 8, v168
	s_lshl_b32 s15, s15, 2
	s_add_u32 s15, s49, s15
	v_ashrrev_i32_e32 v161, 31, v160
	s_addc_u32 s17, s54, 0
	s_lshl_b32 s24, s62, 8
	v_lshl_add_u64 v[164:165], v[160:161], 2, s[6:7]
	s_ashr_i32 s25, s24, 31
	v_mov_b32_e32 v194, 0xbfb8aa3b
	v_mov_b32_e32 v195, 0xbfb8aa3b
	v_mov_b32_e32 v196, 1.0
	v_mov_b32_e32 v197, 1.0
	v_mov_b32_e32 v198, 0x16000
	v_mov_b32_e32 v199, 0
	v_mov_b32_e32 v200, 0x6e000
	v_mov_b32_e32 v201, 0
	global_load_dword v161, v[164:165], off
	global_load_dword v241, v[164:165], off offset:64
	global_load_dword v242, v[164:165], off offset:128
	global_load_dword v243, v[164:165], off offset:192
	global_load_dword v244, v[164:165], off offset:512
	global_load_dword v245, v[164:165], off offset:576
	global_load_dword v246, v[164:165], off offset:640
	global_load_dword v247, v[164:165], off offset:704
	s_lshl_b64 s[24:25], s[24:25], 2
	s_add_u32 s15, s15, s24
	s_addc_u32 s17, s17, s25
	s_add_u32 s24, s15, s61
	s_addc_u32 s25, s17, 0
	global_load_dwordx4 v[112:115], v174, s[24:25]
	global_load_dwordx4 v[116:119], v174, s[24:25] offset:512
	global_load_dwordx4 v[104:107], v174, s[24:25] offset:16
	global_load_dwordx4 v[108:111], v174, s[24:25] offset:528
	v_or_b32_e32 v180, 16, v160
	v_ashrrev_i32_e32 v181, 31, v180
	v_lshl_or_b32 v166, s62, 7, v170
	v_mov_b64_e32 v[162:163], s[36:37]
	v_ashrrev_i32_e32 v167, 31, v166
	v_mad_i64_i32 v[178:179], s[24:25], v160, s60, v[162:163]
	v_lshlrev_b64 v[166:167], 1, v[166:167]
	v_lshl_add_u64 v[178:179], v[178:179], 0, v[166:167]
	s_andn2_b64 vcc, exec, s[2:3]
	s_mov_b64 s[2:3], -1
	s_waitcnt vmcnt(0)
	v_fmamk_f32 v161, v161, 0x3a800000, v175
	v_rsq_f32_e32 v182, v161
	s_nop 0
	v_pk_fma_f32 v[140:141], v[140:141], v[182:183], v[112:113] op_sel_hi:[1,0,1]
	v_pk_fma_f32 v[142:143], v[142:143], v[182:183], v[114:115] op_sel_hi:[1,0,1]
	v_pk_fma_f32 v[136:137], v[136:137], v[182:183], v[104:105] op_sel_hi:[1,0,1]
	v_pk_fma_f32 v[138:139], v[138:139], v[182:183], v[106:107] op_sel_hi:[1,0,1]
	v_pk_fma_f32 v[132:133], v[132:133], v[182:183], v[116:117] op_sel_hi:[1,0,1]
	v_pk_fma_f32 v[134:135], v[134:135], v[182:183], v[118:119] op_sel_hi:[1,0,1]
	v_pk_fma_f32 v[128:129], v[128:129], v[182:183], v[108:109] op_sel_hi:[1,0,1]
	v_pk_fma_f32 v[130:131], v[130:131], v[182:183], v[110:111] op_sel_hi:[1,0,1]
	v_pk_mul_f32 v[182:183], v[140:141], v[194:195]
	v_pk_mul_f32 v[186:187], v[142:143], v[194:195]
	v_pk_mul_f32 v[188:189], v[136:137], v[194:195]
	v_pk_mul_f32 v[190:191], v[138:139], v[194:195]
	v_exp_f32_e32 v182, v182
	v_exp_f32_e32 v183, v183
	v_exp_f32_e32 v186, v186
	v_exp_f32_e32 v187, v187
	v_exp_f32_e32 v188, v188
	v_exp_f32_e32 v189, v189
	v_exp_f32_e32 v190, v190
	v_exp_f32_e32 v191, v191
	v_pk_add_f32 v[182:183], v[182:183], v[196:197]
	v_pk_add_f32 v[186:187], v[186:187], v[196:197]
	v_pk_add_f32 v[188:189], v[188:189], v[196:197]
	v_pk_add_f32 v[190:191], v[190:191], v[196:197]
	v_rcp_f32_e32 v182, v182
	v_rcp_f32_e32 v183, v183
	v_rcp_f32_e32 v186, v186
	v_rcp_f32_e32 v187, v187
	v_rcp_f32_e32 v188, v188
	v_rcp_f32_e32 v189, v189
	v_rcp_f32_e32 v190, v190
	v_rcp_f32_e32 v191, v191
	v_pk_mul_f32 v[140:141], v[140:141], v[182:183]
	v_pk_mul_f32 v[142:143], v[142:143], v[186:187]
	v_pk_mul_f32 v[136:137], v[136:137], v[188:189]
	v_pk_mul_f32 v[138:139], v[138:139], v[190:191]
	v_pk_mul_f32 v[132:133], v[132:133], v[140:141]
	v_pk_mul_f32 v[134:135], v[134:135], v[142:143]
	v_pk_mul_f32 v[136:137], v[128:129], v[136:137]
	v_pk_mul_f32 v[138:139], v[130:131], v[138:139]
	v_cvt_pk_f16_f32 v128, v132, v133
	v_cvt_pk_f16_f32 v129, v134, v135
	v_cvt_pk_f16_f32 v130, v136, v137
	v_cvt_pk_f16_f32 v131, v138, v139
	global_store_dwordx4 v[178:179], v[128:131], off
	s_nop 0
	s_nop 0
	v_or_b32_e32 v128, 32, v160
	v_lshl_add_u64 v[130:131], v[178:179], 0, v[198:199]
	v_fmamk_f32 v129, v241, 0x3a800000, v175
	v_rsq_f32_e32 v132, v129
	v_ashrrev_i32_e32 v129, 31, v128
	v_pk_fma_f32 v[124:125], v[124:125], v[132:133], v[112:113] op_sel_hi:[1,0,1]
	v_pk_fma_f32 v[126:127], v[126:127], v[132:133], v[114:115] op_sel_hi:[1,0,1]
	v_pk_fma_f32 v[120:121], v[120:121], v[132:133], v[104:105] op_sel_hi:[1,0,1]
	v_pk_fma_f32 v[122:123], v[122:123], v[132:133], v[106:107] op_sel_hi:[1,0,1]
	v_pk_fma_f32 v[100:101], v[100:101], v[132:133], v[116:117] op_sel_hi:[1,0,1]
	v_pk_fma_f32 v[102:103], v[102:103], v[132:133], v[118:119] op_sel_hi:[1,0,1]
	v_pk_fma_f32 v[96:97], v[96:97], v[132:133], v[108:109] op_sel_hi:[1,0,1]
	v_pk_fma_f32 v[98:99], v[98:99], v[132:133], v[110:111] op_sel_hi:[1,0,1]
	v_pk_mul_f32 v[132:133], v[124:125], v[194:195]
	v_pk_mul_f32 v[136:137], v[126:127], v[194:195]
	v_pk_mul_f32 v[138:139], v[120:121], v[194:195]
	v_pk_mul_f32 v[140:141], v[122:123], v[194:195]
	v_exp_f32_e32 v132, v132
	v_exp_f32_e32 v133, v133
	v_exp_f32_e32 v136, v136
	v_exp_f32_e32 v137, v137
	v_exp_f32_e32 v138, v138
	v_exp_f32_e32 v139, v139
	v_exp_f32_e32 v140, v140
	v_exp_f32_e32 v141, v141
	v_pk_add_f32 v[132:133], v[132:133], v[196:197]
	v_pk_add_f32 v[136:137], v[136:137], v[196:197]
	v_pk_add_f32 v[138:139], v[138:139], v[196:197]
	v_pk_add_f32 v[140:141], v[140:141], v[196:197]
	v_rcp_f32_e32 v132, v132
	v_rcp_f32_e32 v133, v133
	v_rcp_f32_e32 v136, v136
	v_rcp_f32_e32 v137, v137
	v_rcp_f32_e32 v138, v138
	v_rcp_f32_e32 v139, v139
	v_rcp_f32_e32 v140, v140
	v_rcp_f32_e32 v141, v141
	v_pk_mul_f32 v[124:125], v[124:125], v[132:133]
	v_pk_mul_f32 v[126:127], v[126:127], v[136:137]
	v_pk_mul_f32 v[120:121], v[120:121], v[138:139]
	v_pk_mul_f32 v[122:123], v[122:123], v[140:141]
	v_pk_mul_f32 v[100:101], v[100:101], v[124:125]
	v_pk_mul_f32 v[102:103], v[102:103], v[126:127]
	v_pk_mul_f32 v[120:121], v[96:97], v[120:121]
	v_pk_mul_f32 v[122:123], v[98:99], v[122:123]
	v_cvt_pk_f16_f32 v96, v100, v101
	v_cvt_pk_f16_f32 v97, v102, v103
	v_cvt_pk_f16_f32 v98, v120, v121
	v_cvt_pk_f16_f32 v99, v122, v123
	global_store_dwordx4 v[130:131], v[96:99], off
	s_nop 0
	s_nop 0
	v_or_b32_e32 v96, 48, v160
	v_lshl_add_u64 v[98:99], v[130:131], 0, v[198:199]
	v_fmamk_f32 v97, v242, 0x3a800000, v175
	v_rsq_f32_e32 v100, v97
	v_ashrrev_i32_e32 v97, 31, v96
	v_pk_fma_f32 v[92:93], v[92:93], v[100:101], v[112:113] op_sel_hi:[1,0,1]
	v_pk_fma_f32 v[94:95], v[94:95], v[100:101], v[114:115] op_sel_hi:[1,0,1]
	v_pk_fma_f32 v[88:89], v[88:89], v[100:101], v[104:105] op_sel_hi:[1,0,1]
	v_pk_fma_f32 v[90:91], v[90:91], v[100:101], v[106:107] op_sel_hi:[1,0,1]
	v_pk_fma_f32 v[84:85], v[84:85], v[100:101], v[116:117] op_sel_hi:[1,0,1]
	v_pk_fma_f32 v[86:87], v[86:87], v[100:101], v[118:119] op_sel_hi:[1,0,1]
	v_pk_fma_f32 v[80:81], v[80:81], v[100:101], v[108:109] op_sel_hi:[1,0,1]
	v_pk_fma_f32 v[82:83], v[82:83], v[100:101], v[110:111] op_sel_hi:[1,0,1]
	v_pk_mul_f32 v[100:101], v[92:93], v[194:195]
	v_pk_mul_f32 v[120:121], v[94:95], v[194:195]
	v_pk_mul_f32 v[122:123], v[88:89], v[194:195]
	v_pk_mul_f32 v[124:125], v[90:91], v[194:195]
	v_exp_f32_e32 v100, v100
	v_exp_f32_e32 v101, v101
	v_exp_f32_e32 v120, v120
	v_exp_f32_e32 v121, v121
	v_exp_f32_e32 v122, v122
	v_exp_f32_e32 v123, v123
	v_exp_f32_e32 v124, v124
	v_exp_f32_e32 v125, v125
	v_pk_add_f32 v[100:101], v[100:101], v[196:197]
	v_pk_add_f32 v[120:121], v[120:121], v[196:197]
	v_pk_add_f32 v[122:123], v[122:123], v[196:197]
	v_pk_add_f32 v[124:125], v[124:125], v[196:197]
	v_rcp_f32_e32 v100, v100
	v_rcp_f32_e32 v101, v101
	v_rcp_f32_e32 v120, v120
	v_rcp_f32_e32 v121, v121
	v_rcp_f32_e32 v122, v122
	v_rcp_f32_e32 v123, v123
	v_rcp_f32_e32 v124, v124
	v_rcp_f32_e32 v125, v125
	v_pk_mul_f32 v[92:93], v[92:93], v[100:101]
	v_pk_mul_f32 v[94:95], v[94:95], v[120:121]
	v_pk_mul_f32 v[88:89], v[88:89], v[122:123]
	v_pk_mul_f32 v[90:91], v[90:91], v[124:125]
	v_pk_mul_f32 v[84:85], v[84:85], v[92:93]
	v_pk_mul_f32 v[86:87], v[86:87], v[94:95]
	v_pk_mul_f32 v[88:89], v[80:81], v[88:89]
	v_pk_mul_f32 v[90:91], v[82:83], v[90:91]
	v_cvt_pk_f16_f32 v80, v84, v85
	v_cvt_pk_f16_f32 v81, v86, v87
	v_cvt_pk_f16_f32 v82, v88, v89
	v_cvt_pk_f16_f32 v83, v90, v91
	global_store_dwordx4 v[98:99], v[80:83], off
	s_nop 0
	s_nop 0
	v_lshl_add_u64 v[82:83], v[98:99], 0, v[198:199]
	v_fmamk_f32 v80, v243, 0x3a800000, v175
	v_rsq_f32_e32 v80, v80
	s_nop 0
	v_pk_fma_f32 v[76:77], v[76:77], v[80:81], v[112:113] op_sel_hi:[1,0,1]
	v_pk_fma_f32 v[78:79], v[78:79], v[80:81], v[114:115] op_sel_hi:[1,0,1]
	v_pk_fma_f32 v[72:73], v[72:73], v[80:81], v[104:105] op_sel_hi:[1,0,1]
	v_pk_fma_f32 v[74:75], v[74:75], v[80:81], v[106:107] op_sel_hi:[1,0,1]
	v_pk_fma_f32 v[68:69], v[68:69], v[80:81], v[116:117] op_sel_hi:[1,0,1]
	v_pk_fma_f32 v[70:71], v[70:71], v[80:81], v[118:119] op_sel_hi:[1,0,1]
	v_pk_fma_f32 v[64:65], v[64:65], v[80:81], v[108:109] op_sel_hi:[1,0,1]
	v_pk_fma_f32 v[66:67], v[66:67], v[80:81], v[110:111] op_sel_hi:[1,0,1]
	v_pk_mul_f32 v[80:81], v[76:77], v[194:195]
	v_pk_mul_f32 v[84:85], v[78:79], v[194:195]
	v_pk_mul_f32 v[86:87], v[72:73], v[194:195]
	v_pk_mul_f32 v[88:89], v[74:75], v[194:195]
	v_exp_f32_e32 v80, v80
	v_exp_f32_e32 v81, v81
	v_exp_f32_e32 v84, v84
	v_exp_f32_e32 v85, v85
	v_exp_f32_e32 v86, v86
	v_exp_f32_e32 v87, v87
	v_exp_f32_e32 v88, v88
	v_exp_f32_e32 v89, v89
	v_pk_add_f32 v[80:81], v[80:81], v[196:197]
	v_pk_add_f32 v[84:85], v[84:85], v[196:197]
	v_pk_add_f32 v[86:87], v[86:87], v[196:197]
	v_pk_add_f32 v[88:89], v[88:89], v[196:197]
	v_rcp_f32_e32 v80, v80
	v_rcp_f32_e32 v81, v81
	v_rcp_f32_e32 v84, v84
	v_rcp_f32_e32 v85, v85
	v_rcp_f32_e32 v86, v86
	v_rcp_f32_e32 v87, v87
	v_rcp_f32_e32 v88, v88
	v_rcp_f32_e32 v89, v89
	v_pk_mul_f32 v[76:77], v[76:77], v[80:81]
	v_pk_mul_f32 v[78:79], v[78:79], v[84:85]
	v_pk_mul_f32 v[72:73], v[72:73], v[86:87]
	v_pk_mul_f32 v[74:75], v[74:75], v[88:89]
	v_pk_mul_f32 v[68:69], v[68:69], v[76:77]
	v_pk_mul_f32 v[70:71], v[70:71], v[78:79]
	v_pk_mul_f32 v[72:73], v[64:65], v[72:73]
	v_pk_mul_f32 v[74:75], v[66:67], v[74:75]
	v_cvt_pk_f16_f32 v64, v68, v69
	v_cvt_pk_f16_f32 v65, v70, v71
	v_cvt_pk_f16_f32 v66, v72, v73
	v_cvt_pk_f16_f32 v67, v74, v75
	global_store_dwordx4 v[82:83], v[64:67], off
	s_nop 0
	s_nop 0
	v_add_u32_e32 v65, 0x80, v160
	v_lshl_add_u64 v[66:67], v[82:83], 0, v[200:201]
	v_fmamk_f32 v64, v244, 0x3a800000, v175
	v_rsq_f32_e32 v64, v64
	s_nop 0
	v_pk_fma_f32 v[60:61], v[60:61], v[64:65], v[112:113] op_sel_hi:[1,0,1]
	v_pk_fma_f32 v[62:63], v[62:63], v[64:65], v[114:115] op_sel_hi:[1,0,1]
	v_pk_fma_f32 v[56:57], v[56:57], v[64:65], v[104:105] op_sel_hi:[1,0,1]
	v_pk_fma_f32 v[58:59], v[58:59], v[64:65], v[106:107] op_sel_hi:[1,0,1]
	v_pk_fma_f32 v[52:53], v[52:53], v[64:65], v[116:117] op_sel_hi:[1,0,1]
	v_pk_fma_f32 v[54:55], v[54:55], v[64:65], v[118:119] op_sel_hi:[1,0,1]
	v_pk_fma_f32 v[48:49], v[48:49], v[64:65], v[108:109] op_sel_hi:[1,0,1]
	v_pk_fma_f32 v[50:51], v[50:51], v[64:65], v[110:111] op_sel_hi:[1,0,1]
	v_pk_mul_f32 v[64:65], v[60:61], v[194:195]
	v_pk_mul_f32 v[68:69], v[62:63], v[194:195]
	v_pk_mul_f32 v[70:71], v[56:57], v[194:195]
	v_pk_mul_f32 v[72:73], v[58:59], v[194:195]
	v_exp_f32_e32 v64, v64
	v_exp_f32_e32 v65, v65
	v_exp_f32_e32 v68, v68
	v_exp_f32_e32 v69, v69
	v_exp_f32_e32 v70, v70
	v_exp_f32_e32 v71, v71
	v_exp_f32_e32 v72, v72
	v_exp_f32_e32 v73, v73
	v_pk_add_f32 v[64:65], v[64:65], v[196:197]
	v_pk_add_f32 v[68:69], v[68:69], v[196:197]
	v_pk_add_f32 v[70:71], v[70:71], v[196:197]
	v_pk_add_f32 v[72:73], v[72:73], v[196:197]
	v_rcp_f32_e32 v64, v64
	v_rcp_f32_e32 v65, v65
	v_rcp_f32_e32 v68, v68
	v_rcp_f32_e32 v69, v69
	v_rcp_f32_e32 v70, v70
	v_rcp_f32_e32 v71, v71
	v_rcp_f32_e32 v72, v72
	v_rcp_f32_e32 v73, v73
	v_pk_mul_f32 v[60:61], v[60:61], v[64:65]
	v_pk_mul_f32 v[62:63], v[62:63], v[68:69]
	v_pk_mul_f32 v[56:57], v[56:57], v[70:71]
	v_pk_mul_f32 v[58:59], v[58:59], v[72:73]
	v_pk_mul_f32 v[52:53], v[52:53], v[60:61]
	v_pk_mul_f32 v[54:55], v[54:55], v[62:63]
	v_pk_mul_f32 v[56:57], v[48:49], v[56:57]
	v_pk_mul_f32 v[58:59], v[50:51], v[58:59]
	v_cvt_pk_f16_f32 v48, v52, v53
	v_cvt_pk_f16_f32 v49, v54, v55
	v_cvt_pk_f16_f32 v50, v56, v57
	v_cvt_pk_f16_f32 v51, v58, v59
	global_store_dwordx4 v[66:67], v[48:51], off
	s_nop 0
	s_nop 0
	v_add_u32_e32 v49, 0x90, v160
	v_lshl_add_u64 v[50:51], v[66:67], 0, v[198:199]
	v_fmamk_f32 v48, v245, 0x3a800000, v175
	v_rsq_f32_e32 v48, v48
	s_nop 0
	v_pk_fma_f32 v[44:45], v[44:45], v[48:49], v[112:113] op_sel_hi:[1,0,1]
	v_pk_fma_f32 v[46:47], v[46:47], v[48:49], v[114:115] op_sel_hi:[1,0,1]
	v_pk_fma_f32 v[40:41], v[40:41], v[48:49], v[104:105] op_sel_hi:[1,0,1]
	v_pk_fma_f32 v[42:43], v[42:43], v[48:49], v[106:107] op_sel_hi:[1,0,1]
	v_pk_fma_f32 v[36:37], v[36:37], v[48:49], v[116:117] op_sel_hi:[1,0,1]
	v_pk_fma_f32 v[38:39], v[38:39], v[48:49], v[118:119] op_sel_hi:[1,0,1]
	v_pk_fma_f32 v[32:33], v[32:33], v[48:49], v[108:109] op_sel_hi:[1,0,1]
	v_pk_fma_f32 v[34:35], v[34:35], v[48:49], v[110:111] op_sel_hi:[1,0,1]
	v_pk_mul_f32 v[48:49], v[44:45], v[194:195]
	v_pk_mul_f32 v[52:53], v[46:47], v[194:195]
	v_pk_mul_f32 v[54:55], v[40:41], v[194:195]
	v_pk_mul_f32 v[56:57], v[42:43], v[194:195]
	v_exp_f32_e32 v48, v48
	v_exp_f32_e32 v49, v49
	v_exp_f32_e32 v52, v52
	v_exp_f32_e32 v53, v53
	v_exp_f32_e32 v54, v54
	v_exp_f32_e32 v55, v55
	v_exp_f32_e32 v56, v56
	v_exp_f32_e32 v57, v57
	v_pk_add_f32 v[48:49], v[48:49], v[196:197]
	v_pk_add_f32 v[52:53], v[52:53], v[196:197]
	v_pk_add_f32 v[54:55], v[54:55], v[196:197]
	v_pk_add_f32 v[56:57], v[56:57], v[196:197]
	v_rcp_f32_e32 v48, v48
	v_rcp_f32_e32 v49, v49
	v_rcp_f32_e32 v52, v52
	v_rcp_f32_e32 v53, v53
	v_rcp_f32_e32 v54, v54
	v_rcp_f32_e32 v55, v55
	v_rcp_f32_e32 v56, v56
	v_rcp_f32_e32 v57, v57
	v_pk_mul_f32 v[44:45], v[44:45], v[48:49]
	v_pk_mul_f32 v[46:47], v[46:47], v[52:53]
	v_pk_mul_f32 v[40:41], v[40:41], v[54:55]
	v_pk_mul_f32 v[42:43], v[42:43], v[56:57]
	v_pk_mul_f32 v[36:37], v[36:37], v[44:45]
	v_pk_mul_f32 v[38:39], v[38:39], v[46:47]
	v_pk_mul_f32 v[40:41], v[32:33], v[40:41]
	v_pk_mul_f32 v[42:43], v[34:35], v[42:43]
	v_cvt_pk_f16_f32 v32, v36, v37
	v_cvt_pk_f16_f32 v33, v38, v39
	v_cvt_pk_f16_f32 v34, v40, v41
	v_cvt_pk_f16_f32 v35, v42, v43
	global_store_dwordx4 v[50:51], v[32:35], off
	s_nop 0
	s_nop 0
	v_add_u32_e32 v33, 0xa0, v160
	v_lshl_add_u64 v[34:35], v[50:51], 0, v[198:199]
	v_fmamk_f32 v32, v246, 0x3a800000, v175
	v_rsq_f32_e32 v32, v32
	s_nop 0
	v_pk_fma_f32 v[28:29], v[28:29], v[32:33], v[112:113] op_sel_hi:[1,0,1]
	v_pk_fma_f32 v[30:31], v[30:31], v[32:33], v[114:115] op_sel_hi:[1,0,1]
	v_pk_fma_f32 v[24:25], v[24:25], v[32:33], v[104:105] op_sel_hi:[1,0,1]
	v_pk_fma_f32 v[26:27], v[26:27], v[32:33], v[106:107] op_sel_hi:[1,0,1]
	v_pk_fma_f32 v[20:21], v[20:21], v[32:33], v[116:117] op_sel_hi:[1,0,1]
	v_pk_fma_f32 v[22:23], v[22:23], v[32:33], v[118:119] op_sel_hi:[1,0,1]
	v_pk_fma_f32 v[16:17], v[16:17], v[32:33], v[108:109] op_sel_hi:[1,0,1]
	v_pk_fma_f32 v[18:19], v[18:19], v[32:33], v[110:111] op_sel_hi:[1,0,1]
	v_pk_mul_f32 v[32:33], v[28:29], v[194:195]
	v_pk_mul_f32 v[36:37], v[30:31], v[194:195]
	v_pk_mul_f32 v[38:39], v[24:25], v[194:195]
	v_pk_mul_f32 v[40:41], v[26:27], v[194:195]
	v_exp_f32_e32 v32, v32
	v_exp_f32_e32 v33, v33
	v_exp_f32_e32 v36, v36
	v_exp_f32_e32 v37, v37
	v_exp_f32_e32 v38, v38
	v_exp_f32_e32 v39, v39
	v_exp_f32_e32 v40, v40
	v_exp_f32_e32 v41, v41
	v_pk_add_f32 v[32:33], v[32:33], v[196:197]
	v_pk_add_f32 v[36:37], v[36:37], v[196:197]
	v_pk_add_f32 v[38:39], v[38:39], v[196:197]
	v_pk_add_f32 v[40:41], v[40:41], v[196:197]
	v_rcp_f32_e32 v32, v32
	v_rcp_f32_e32 v33, v33
	v_rcp_f32_e32 v36, v36
	v_rcp_f32_e32 v37, v37
	v_rcp_f32_e32 v38, v38
	v_rcp_f32_e32 v39, v39
	v_rcp_f32_e32 v40, v40
	v_rcp_f32_e32 v41, v41
	v_pk_mul_f32 v[28:29], v[28:29], v[32:33]
	v_pk_mul_f32 v[30:31], v[30:31], v[36:37]
	v_pk_mul_f32 v[24:25], v[24:25], v[38:39]
	v_pk_mul_f32 v[26:27], v[26:27], v[40:41]
	v_pk_mul_f32 v[20:21], v[20:21], v[28:29]
	v_pk_mul_f32 v[22:23], v[22:23], v[30:31]
	v_pk_mul_f32 v[24:25], v[16:17], v[24:25]
	v_pk_mul_f32 v[26:27], v[18:19], v[26:27]
	v_cvt_pk_f16_f32 v16, v20, v21
	v_cvt_pk_f16_f32 v17, v22, v23
	v_cvt_pk_f16_f32 v18, v24, v25
	v_cvt_pk_f16_f32 v19, v26, v27
	global_store_dwordx4 v[34:35], v[16:19], off
	s_nop 0
	s_nop 0
	v_add_u32_e32 v17, 0xb0, v160
	v_lshl_add_u64 v[18:19], v[34:35], 0, v[198:199]
	v_fmamk_f32 v16, v247, 0x3a800000, v175
	v_rsq_f32_e32 v16, v16
	s_nop 0
	v_pk_fma_f32 v[12:13], v[12:13], v[16:17], v[112:113] op_sel_hi:[1,0,1]
	v_pk_fma_f32 v[14:15], v[14:15], v[16:17], v[114:115] op_sel_hi:[1,0,1]
	v_pk_fma_f32 v[8:9], v[8:9], v[16:17], v[104:105] op_sel_hi:[1,0,1]
	v_pk_fma_f32 v[10:11], v[10:11], v[16:17], v[106:107] op_sel_hi:[1,0,1]
	v_pk_fma_f32 v[4:5], v[4:5], v[16:17], v[116:117] op_sel_hi:[1,0,1]
	v_pk_fma_f32 v[6:7], v[6:7], v[16:17], v[118:119] op_sel_hi:[1,0,1]
	v_pk_fma_f32 v[0:1], v[0:1], v[16:17], v[108:109] op_sel_hi:[1,0,1]
	v_pk_fma_f32 v[2:3], v[2:3], v[16:17], v[110:111] op_sel_hi:[1,0,1]
	v_pk_mul_f32 v[16:17], v[12:13], v[194:195]
	v_pk_mul_f32 v[20:21], v[14:15], v[194:195]
	v_pk_mul_f32 v[22:23], v[8:9], v[194:195]
	v_pk_mul_f32 v[24:25], v[10:11], v[194:195]
	v_exp_f32_e32 v16, v16
	v_exp_f32_e32 v17, v17
	v_exp_f32_e32 v20, v20
	v_exp_f32_e32 v21, v21
	v_exp_f32_e32 v22, v22
	v_exp_f32_e32 v23, v23
	v_exp_f32_e32 v24, v24
	v_exp_f32_e32 v25, v25
	v_pk_add_f32 v[16:17], v[16:17], v[196:197]
	v_pk_add_f32 v[20:21], v[20:21], v[196:197]
	v_pk_add_f32 v[22:23], v[22:23], v[196:197]
	v_pk_add_f32 v[24:25], v[24:25], v[196:197]
	v_rcp_f32_e32 v16, v16
	v_rcp_f32_e32 v17, v17
	v_rcp_f32_e32 v20, v20
	v_rcp_f32_e32 v21, v21
	v_rcp_f32_e32 v22, v22
	v_rcp_f32_e32 v23, v23
	v_rcp_f32_e32 v24, v24
	v_rcp_f32_e32 v25, v25
	v_pk_mul_f32 v[12:13], v[12:13], v[16:17]
	v_pk_mul_f32 v[14:15], v[14:15], v[20:21]
	v_pk_mul_f32 v[8:9], v[8:9], v[22:23]
	v_pk_mul_f32 v[10:11], v[10:11], v[24:25]
	v_pk_mul_f32 v[4:5], v[4:5], v[12:13]
	v_pk_mul_f32 v[6:7], v[6:7], v[14:15]
	v_pk_mul_f32 v[8:9], v[0:1], v[8:9]
	v_pk_mul_f32 v[10:11], v[2:3], v[10:11]
	v_cvt_pk_f16_f32 v0, v4, v5
	v_cvt_pk_f16_f32 v1, v6, v7
	v_cvt_pk_f16_f32 v2, v8, v9
	v_cvt_pk_f16_f32 v3, v10, v11
	global_store_dwordx4 v[18:19], v[0:3], off
	s_cbranch_vccnz .LBB0_865
	s_andn2_b64 vcc, exec, s[4:5]
	s_cbranch_vccnz .LBB0_864
	s_barrier
	s_branch .LBB0_864

.LBB0_1588:
	s_cmp_lt_i32 s22, 64
	s_cselect_b32 s15, s57, 0x2c00
	s_cmp_gt_i32 s22, 31
	s_cselect_b32 s15, s15, 0
	v_lshl_add_u32 v160, s22, 8, v168
	s_lshl_b32 s15, s15, 2
	s_add_u32 s15, s50, s15
	v_ashrrev_i32_e32 v161, 31, v160
	s_addc_u32 s17, s51, 0
	s_lshl_b32 s24, s59, 8
	v_lshl_add_u64 v[164:165], v[160:161], 2, s[6:7]
	s_ashr_i32 s25, s24, 31
	v_mov_b32_e32 v194, 0xbfb8aa3b
	v_mov_b32_e32 v195, 0xbfb8aa3b
	v_mov_b32_e32 v196, 1.0
	v_mov_b32_e32 v197, 1.0
	v_mov_b32_e32 v198, 0x16000
	v_mov_b32_e32 v199, 0
	v_mov_b32_e32 v200, 0x6e000
	v_mov_b32_e32 v201, 0
	global_load_dword v161, v[164:165], off
	global_load_dword v241, v[164:165], off offset:64
	global_load_dword v242, v[164:165], off offset:128
	global_load_dword v243, v[164:165], off offset:192
	global_load_dword v244, v[164:165], off offset:512
	global_load_dword v245, v[164:165], off offset:576
	global_load_dword v246, v[164:165], off offset:640
	global_load_dword v247, v[164:165], off offset:704
	s_lshl_b64 s[24:25], s[24:25], 2
	s_add_u32 s15, s15, s24
	s_addc_u32 s17, s17, s25
	s_add_u32 s24, s15, s58
	s_addc_u32 s25, s17, 0
	global_load_dwordx4 v[112:115], v174, s[24:25]
	global_load_dwordx4 v[116:119], v174, s[24:25] offset:512
	global_load_dwordx4 v[104:107], v174, s[24:25] offset:16
	global_load_dwordx4 v[108:111], v174, s[24:25] offset:528
	v_or_b32_e32 v180, 16, v160
	v_ashrrev_i32_e32 v181, 31, v180
	v_lshl_or_b32 v166, s59, 7, v170
	v_mov_b64_e32 v[162:163], s[36:37]
	v_ashrrev_i32_e32 v167, 31, v166
	v_mad_i64_i32 v[178:179], s[24:25], v160, s57, v[162:163]
	v_lshlrev_b64 v[166:167], 1, v[166:167]
	v_lshl_add_u64 v[178:179], v[178:179], 0, v[166:167]
	s_andn2_b64 vcc, exec, s[2:3]
	s_mov_b64 s[2:3], -1
	s_waitcnt vmcnt(0)
	v_fmamk_f32 v161, v161, 0x3a800000, v175
	v_rsq_f32_e32 v182, v161
	s_nop 0
	v_pk_fma_f32 v[140:141], v[140:141], v[182:183], v[112:113] op_sel_hi:[1,0,1]
	v_pk_fma_f32 v[142:143], v[142:143], v[182:183], v[114:115] op_sel_hi:[1,0,1]
	v_pk_fma_f32 v[136:137], v[136:137], v[182:183], v[104:105] op_sel_hi:[1,0,1]
	v_pk_fma_f32 v[138:139], v[138:139], v[182:183], v[106:107] op_sel_hi:[1,0,1]
	v_pk_fma_f32 v[132:133], v[132:133], v[182:183], v[116:117] op_sel_hi:[1,0,1]
	v_pk_fma_f32 v[134:135], v[134:135], v[182:183], v[118:119] op_sel_hi:[1,0,1]
	v_pk_fma_f32 v[128:129], v[128:129], v[182:183], v[108:109] op_sel_hi:[1,0,1]
	v_pk_fma_f32 v[130:131], v[130:131], v[182:183], v[110:111] op_sel_hi:[1,0,1]
	v_pk_mul_f32 v[182:183], v[140:141], v[194:195]
	v_pk_mul_f32 v[186:187], v[142:143], v[194:195]
	v_pk_mul_f32 v[188:189], v[136:137], v[194:195]
	v_pk_mul_f32 v[190:191], v[138:139], v[194:195]
	v_exp_f32_e32 v182, v182
	v_exp_f32_e32 v183, v183
	v_exp_f32_e32 v186, v186
	v_exp_f32_e32 v187, v187
	v_exp_f32_e32 v188, v188
	v_exp_f32_e32 v189, v189
	v_exp_f32_e32 v190, v190
	v_exp_f32_e32 v191, v191
	v_pk_add_f32 v[182:183], v[182:183], v[196:197]
	v_pk_add_f32 v[186:187], v[186:187], v[196:197]
	v_pk_add_f32 v[188:189], v[188:189], v[196:197]
	v_pk_add_f32 v[190:191], v[190:191], v[196:197]
	v_rcp_f32_e32 v182, v182
	v_rcp_f32_e32 v183, v183
	v_rcp_f32_e32 v186, v186
	v_rcp_f32_e32 v187, v187
	v_rcp_f32_e32 v188, v188
	v_rcp_f32_e32 v189, v189
	v_rcp_f32_e32 v190, v190
	v_rcp_f32_e32 v191, v191
	v_pk_mul_f32 v[140:141], v[140:141], v[182:183]
	v_pk_mul_f32 v[142:143], v[142:143], v[186:187]
	v_pk_mul_f32 v[136:137], v[136:137], v[188:189]
	v_pk_mul_f32 v[138:139], v[138:139], v[190:191]
	v_pk_mul_f32 v[132:133], v[132:133], v[140:141]
	v_pk_mul_f32 v[134:135], v[134:135], v[142:143]
	v_pk_mul_f32 v[136:137], v[128:129], v[136:137]
	v_pk_mul_f32 v[138:139], v[130:131], v[138:139]
	v_cvt_pk_f16_f32 v128, v132, v133
	v_cvt_pk_f16_f32 v129, v134, v135
	v_cvt_pk_f16_f32 v130, v136, v137
	v_cvt_pk_f16_f32 v131, v138, v139
	global_store_dwordx4 v[178:179], v[128:131], off
	s_nop 0
	s_nop 0
	v_or_b32_e32 v128, 32, v160
	v_lshl_add_u64 v[130:131], v[178:179], 0, v[198:199]
	v_fmamk_f32 v129, v241, 0x3a800000, v175
	v_rsq_f32_e32 v132, v129
	v_ashrrev_i32_e32 v129, 31, v128
	v_pk_fma_f32 v[124:125], v[124:125], v[132:133], v[112:113] op_sel_hi:[1,0,1]
	v_pk_fma_f32 v[126:127], v[126:127], v[132:133], v[114:115] op_sel_hi:[1,0,1]
	v_pk_fma_f32 v[120:121], v[120:121], v[132:133], v[104:105] op_sel_hi:[1,0,1]
	v_pk_fma_f32 v[122:123], v[122:123], v[132:133], v[106:107] op_sel_hi:[1,0,1]
	v_pk_fma_f32 v[100:101], v[100:101], v[132:133], v[116:117] op_sel_hi:[1,0,1]
	v_pk_fma_f32 v[102:103], v[102:103], v[132:133], v[118:119] op_sel_hi:[1,0,1]
	v_pk_fma_f32 v[96:97], v[96:97], v[132:133], v[108:109] op_sel_hi:[1,0,1]
	v_pk_fma_f32 v[98:99], v[98:99], v[132:133], v[110:111] op_sel_hi:[1,0,1]
	v_pk_mul_f32 v[132:133], v[124:125], v[194:195]
	v_pk_mul_f32 v[136:137], v[126:127], v[194:195]
	v_pk_mul_f32 v[138:139], v[120:121], v[194:195]
	v_pk_mul_f32 v[140:141], v[122:123], v[194:195]
	v_exp_f32_e32 v132, v132
	v_exp_f32_e32 v133, v133
	v_exp_f32_e32 v136, v136
	v_exp_f32_e32 v137, v137
	v_exp_f32_e32 v138, v138
	v_exp_f32_e32 v139, v139
	v_exp_f32_e32 v140, v140
	v_exp_f32_e32 v141, v141
	v_pk_add_f32 v[132:133], v[132:133], v[196:197]
	v_pk_add_f32 v[136:137], v[136:137], v[196:197]
	v_pk_add_f32 v[138:139], v[138:139], v[196:197]
	v_pk_add_f32 v[140:141], v[140:141], v[196:197]
	v_rcp_f32_e32 v132, v132
	v_rcp_f32_e32 v133, v133
	v_rcp_f32_e32 v136, v136
	v_rcp_f32_e32 v137, v137
	v_rcp_f32_e32 v138, v138
	v_rcp_f32_e32 v139, v139
	v_rcp_f32_e32 v140, v140
	v_rcp_f32_e32 v141, v141
	v_pk_mul_f32 v[124:125], v[124:125], v[132:133]
	v_pk_mul_f32 v[126:127], v[126:127], v[136:137]
	v_pk_mul_f32 v[120:121], v[120:121], v[138:139]
	v_pk_mul_f32 v[122:123], v[122:123], v[140:141]
	v_pk_mul_f32 v[100:101], v[100:101], v[124:125]
	v_pk_mul_f32 v[102:103], v[102:103], v[126:127]
	v_pk_mul_f32 v[120:121], v[96:97], v[120:121]
	v_pk_mul_f32 v[122:123], v[98:99], v[122:123]
	v_cvt_pk_f16_f32 v96, v100, v101
	v_cvt_pk_f16_f32 v97, v102, v103
	v_cvt_pk_f16_f32 v98, v120, v121
	v_cvt_pk_f16_f32 v99, v122, v123
	global_store_dwordx4 v[130:131], v[96:99], off
	s_nop 0
	s_nop 0
	v_or_b32_e32 v96, 48, v160
	v_lshl_add_u64 v[98:99], v[130:131], 0, v[198:199]
	v_fmamk_f32 v97, v242, 0x3a800000, v175
	v_rsq_f32_e32 v100, v97
	v_ashrrev_i32_e32 v97, 31, v96
	v_pk_fma_f32 v[92:93], v[92:93], v[100:101], v[112:113] op_sel_hi:[1,0,1]
	v_pk_fma_f32 v[94:95], v[94:95], v[100:101], v[114:115] op_sel_hi:[1,0,1]
	v_pk_fma_f32 v[88:89], v[88:89], v[100:101], v[104:105] op_sel_hi:[1,0,1]
	v_pk_fma_f32 v[90:91], v[90:91], v[100:101], v[106:107] op_sel_hi:[1,0,1]
	v_pk_fma_f32 v[84:85], v[84:85], v[100:101], v[116:117] op_sel_hi:[1,0,1]
	v_pk_fma_f32 v[86:87], v[86:87], v[100:101], v[118:119] op_sel_hi:[1,0,1]
	v_pk_fma_f32 v[80:81], v[80:81], v[100:101], v[108:109] op_sel_hi:[1,0,1]
	v_pk_fma_f32 v[82:83], v[82:83], v[100:101], v[110:111] op_sel_hi:[1,0,1]
	v_pk_mul_f32 v[100:101], v[92:93], v[194:195]
	v_pk_mul_f32 v[120:121], v[94:95], v[194:195]
	v_pk_mul_f32 v[122:123], v[88:89], v[194:195]
	v_pk_mul_f32 v[124:125], v[90:91], v[194:195]
	v_exp_f32_e32 v100, v100
	v_exp_f32_e32 v101, v101
	v_exp_f32_e32 v120, v120
	v_exp_f32_e32 v121, v121
	v_exp_f32_e32 v122, v122
	v_exp_f32_e32 v123, v123
	v_exp_f32_e32 v124, v124
	v_exp_f32_e32 v125, v125
	v_pk_add_f32 v[100:101], v[100:101], v[196:197]
	v_pk_add_f32 v[120:121], v[120:121], v[196:197]
	v_pk_add_f32 v[122:123], v[122:123], v[196:197]
	v_pk_add_f32 v[124:125], v[124:125], v[196:197]
	v_rcp_f32_e32 v100, v100
	v_rcp_f32_e32 v101, v101
	v_rcp_f32_e32 v120, v120
	v_rcp_f32_e32 v121, v121
	v_rcp_f32_e32 v122, v122
	v_rcp_f32_e32 v123, v123
	v_rcp_f32_e32 v124, v124
	v_rcp_f32_e32 v125, v125
	v_pk_mul_f32 v[92:93], v[92:93], v[100:101]
	v_pk_mul_f32 v[94:95], v[94:95], v[120:121]
	v_pk_mul_f32 v[88:89], v[88:89], v[122:123]
	v_pk_mul_f32 v[90:91], v[90:91], v[124:125]
	v_pk_mul_f32 v[84:85], v[84:85], v[92:93]
	v_pk_mul_f32 v[86:87], v[86:87], v[94:95]
	v_pk_mul_f32 v[88:89], v[80:81], v[88:89]
	v_pk_mul_f32 v[90:91], v[82:83], v[90:91]
	v_cvt_pk_f16_f32 v80, v84, v85
	v_cvt_pk_f16_f32 v81, v86, v87
	v_cvt_pk_f16_f32 v82, v88, v89
	v_cvt_pk_f16_f32 v83, v90, v91
	global_store_dwordx4 v[98:99], v[80:83], off
	s_nop 0
	s_nop 0
	v_lshl_add_u64 v[82:83], v[98:99], 0, v[198:199]
	v_fmamk_f32 v80, v243, 0x3a800000, v175
	v_rsq_f32_e32 v80, v80
	s_nop 0
	v_pk_fma_f32 v[76:77], v[76:77], v[80:81], v[112:113] op_sel_hi:[1,0,1]
	v_pk_fma_f32 v[78:79], v[78:79], v[80:81], v[114:115] op_sel_hi:[1,0,1]
	v_pk_fma_f32 v[72:73], v[72:73], v[80:81], v[104:105] op_sel_hi:[1,0,1]
	v_pk_fma_f32 v[74:75], v[74:75], v[80:81], v[106:107] op_sel_hi:[1,0,1]
	v_pk_fma_f32 v[68:69], v[68:69], v[80:81], v[116:117] op_sel_hi:[1,0,1]
	v_pk_fma_f32 v[70:71], v[70:71], v[80:81], v[118:119] op_sel_hi:[1,0,1]
	v_pk_fma_f32 v[64:65], v[64:65], v[80:81], v[108:109] op_sel_hi:[1,0,1]
	v_pk_fma_f32 v[66:67], v[66:67], v[80:81], v[110:111] op_sel_hi:[1,0,1]
	v_pk_mul_f32 v[80:81], v[76:77], v[194:195]
	v_pk_mul_f32 v[84:85], v[78:79], v[194:195]
	v_pk_mul_f32 v[86:87], v[72:73], v[194:195]
	v_pk_mul_f32 v[88:89], v[74:75], v[194:195]
	v_exp_f32_e32 v80, v80
	v_exp_f32_e32 v81, v81
	v_exp_f32_e32 v84, v84
	v_exp_f32_e32 v85, v85
	v_exp_f32_e32 v86, v86
	v_exp_f32_e32 v87, v87
	v_exp_f32_e32 v88, v88
	v_exp_f32_e32 v89, v89
	v_pk_add_f32 v[80:81], v[80:81], v[196:197]
	v_pk_add_f32 v[84:85], v[84:85], v[196:197]
	v_pk_add_f32 v[86:87], v[86:87], v[196:197]
	v_pk_add_f32 v[88:89], v[88:89], v[196:197]
	v_rcp_f32_e32 v80, v80
	v_rcp_f32_e32 v81, v81
	v_rcp_f32_e32 v84, v84
	v_rcp_f32_e32 v85, v85
	v_rcp_f32_e32 v86, v86
	v_rcp_f32_e32 v87, v87
	v_rcp_f32_e32 v88, v88
	v_rcp_f32_e32 v89, v89
	v_pk_mul_f32 v[76:77], v[76:77], v[80:81]
	v_pk_mul_f32 v[78:79], v[78:79], v[84:85]
	v_pk_mul_f32 v[72:73], v[72:73], v[86:87]
	v_pk_mul_f32 v[74:75], v[74:75], v[88:89]
	v_pk_mul_f32 v[68:69], v[68:69], v[76:77]
	v_pk_mul_f32 v[70:71], v[70:71], v[78:79]
	v_pk_mul_f32 v[72:73], v[64:65], v[72:73]
	v_pk_mul_f32 v[74:75], v[66:67], v[74:75]
	v_cvt_pk_f16_f32 v64, v68, v69
	v_cvt_pk_f16_f32 v65, v70, v71
	v_cvt_pk_f16_f32 v66, v72, v73
	v_cvt_pk_f16_f32 v67, v74, v75
	global_store_dwordx4 v[82:83], v[64:67], off
	s_nop 0
	s_nop 0
	v_add_u32_e32 v65, 0x80, v160
	v_lshl_add_u64 v[66:67], v[82:83], 0, v[200:201]
	v_fmamk_f32 v64, v244, 0x3a800000, v175
	v_rsq_f32_e32 v64, v64
	s_nop 0
	v_pk_fma_f32 v[60:61], v[60:61], v[64:65], v[112:113] op_sel_hi:[1,0,1]
	v_pk_fma_f32 v[62:63], v[62:63], v[64:65], v[114:115] op_sel_hi:[1,0,1]
	v_pk_fma_f32 v[56:57], v[56:57], v[64:65], v[104:105] op_sel_hi:[1,0,1]
	v_pk_fma_f32 v[58:59], v[58:59], v[64:65], v[106:107] op_sel_hi:[1,0,1]
	v_pk_fma_f32 v[52:53], v[52:53], v[64:65], v[116:117] op_sel_hi:[1,0,1]
	v_pk_fma_f32 v[54:55], v[54:55], v[64:65], v[118:119] op_sel_hi:[1,0,1]
	v_pk_fma_f32 v[48:49], v[48:49], v[64:65], v[108:109] op_sel_hi:[1,0,1]
	v_pk_fma_f32 v[50:51], v[50:51], v[64:65], v[110:111] op_sel_hi:[1,0,1]
	v_pk_mul_f32 v[64:65], v[60:61], v[194:195]
	v_pk_mul_f32 v[68:69], v[62:63], v[194:195]
	v_pk_mul_f32 v[70:71], v[56:57], v[194:195]
	v_pk_mul_f32 v[72:73], v[58:59], v[194:195]
	v_exp_f32_e32 v64, v64
	v_exp_f32_e32 v65, v65
	v_exp_f32_e32 v68, v68
	v_exp_f32_e32 v69, v69
	v_exp_f32_e32 v70, v70
	v_exp_f32_e32 v71, v71
	v_exp_f32_e32 v72, v72
	v_exp_f32_e32 v73, v73
	v_pk_add_f32 v[64:65], v[64:65], v[196:197]
	v_pk_add_f32 v[68:69], v[68:69], v[196:197]
	v_pk_add_f32 v[70:71], v[70:71], v[196:197]
	v_pk_add_f32 v[72:73], v[72:73], v[196:197]
	v_rcp_f32_e32 v64, v64
	v_rcp_f32_e32 v65, v65
	v_rcp_f32_e32 v68, v68
	v_rcp_f32_e32 v69, v69
	v_rcp_f32_e32 v70, v70
	v_rcp_f32_e32 v71, v71
	v_rcp_f32_e32 v72, v72
	v_rcp_f32_e32 v73, v73
	v_pk_mul_f32 v[60:61], v[60:61], v[64:65]
	v_pk_mul_f32 v[62:63], v[62:63], v[68:69]
	v_pk_mul_f32 v[56:57], v[56:57], v[70:71]
	v_pk_mul_f32 v[58:59], v[58:59], v[72:73]
	v_pk_mul_f32 v[52:53], v[52:53], v[60:61]
	v_pk_mul_f32 v[54:55], v[54:55], v[62:63]
	v_pk_mul_f32 v[56:57], v[48:49], v[56:57]
	v_pk_mul_f32 v[58:59], v[50:51], v[58:59]
	v_cvt_pk_f16_f32 v48, v52, v53
	v_cvt_pk_f16_f32 v49, v54, v55
	v_cvt_pk_f16_f32 v50, v56, v57
	v_cvt_pk_f16_f32 v51, v58, v59
	global_store_dwordx4 v[66:67], v[48:51], off
	s_nop 0
	s_nop 0
	v_add_u32_e32 v49, 0x90, v160
	v_lshl_add_u64 v[50:51], v[66:67], 0, v[198:199]
	v_fmamk_f32 v48, v245, 0x3a800000, v175
	v_rsq_f32_e32 v48, v48
	s_nop 0
	v_pk_fma_f32 v[44:45], v[44:45], v[48:49], v[112:113] op_sel_hi:[1,0,1]
	v_pk_fma_f32 v[46:47], v[46:47], v[48:49], v[114:115] op_sel_hi:[1,0,1]
	v_pk_fma_f32 v[40:41], v[40:41], v[48:49], v[104:105] op_sel_hi:[1,0,1]
	v_pk_fma_f32 v[42:43], v[42:43], v[48:49], v[106:107] op_sel_hi:[1,0,1]
	v_pk_fma_f32 v[36:37], v[36:37], v[48:49], v[116:117] op_sel_hi:[1,0,1]
	v_pk_fma_f32 v[38:39], v[38:39], v[48:49], v[118:119] op_sel_hi:[1,0,1]
	v_pk_fma_f32 v[32:33], v[32:33], v[48:49], v[108:109] op_sel_hi:[1,0,1]
	v_pk_fma_f32 v[34:35], v[34:35], v[48:49], v[110:111] op_sel_hi:[1,0,1]
	v_pk_mul_f32 v[48:49], v[44:45], v[194:195]
	v_pk_mul_f32 v[52:53], v[46:47], v[194:195]
	v_pk_mul_f32 v[54:55], v[40:41], v[194:195]
	v_pk_mul_f32 v[56:57], v[42:43], v[194:195]
	v_exp_f32_e32 v48, v48
	v_exp_f32_e32 v49, v49
	v_exp_f32_e32 v52, v52
	v_exp_f32_e32 v53, v53
	v_exp_f32_e32 v54, v54
	v_exp_f32_e32 v55, v55
	v_exp_f32_e32 v56, v56
	v_exp_f32_e32 v57, v57
	v_pk_add_f32 v[48:49], v[48:49], v[196:197]
	v_pk_add_f32 v[52:53], v[52:53], v[196:197]
	v_pk_add_f32 v[54:55], v[54:55], v[196:197]
	v_pk_add_f32 v[56:57], v[56:57], v[196:197]
	v_rcp_f32_e32 v48, v48
	v_rcp_f32_e32 v49, v49
	v_rcp_f32_e32 v52, v52
	v_rcp_f32_e32 v53, v53
	v_rcp_f32_e32 v54, v54
	v_rcp_f32_e32 v55, v55
	v_rcp_f32_e32 v56, v56
	v_rcp_f32_e32 v57, v57
	v_pk_mul_f32 v[44:45], v[44:45], v[48:49]
	v_pk_mul_f32 v[46:47], v[46:47], v[52:53]
	v_pk_mul_f32 v[40:41], v[40:41], v[54:55]
	v_pk_mul_f32 v[42:43], v[42:43], v[56:57]
	v_pk_mul_f32 v[36:37], v[36:37], v[44:45]
	v_pk_mul_f32 v[38:39], v[38:39], v[46:47]
	v_pk_mul_f32 v[40:41], v[32:33], v[40:41]
	v_pk_mul_f32 v[42:43], v[34:35], v[42:43]
	v_cvt_pk_f16_f32 v32, v36, v37
	v_cvt_pk_f16_f32 v33, v38, v39
	v_cvt_pk_f16_f32 v34, v40, v41
	v_cvt_pk_f16_f32 v35, v42, v43
	global_store_dwordx4 v[50:51], v[32:35], off
	s_nop 0
	s_nop 0
	v_add_u32_e32 v33, 0xa0, v160
	v_lshl_add_u64 v[34:35], v[50:51], 0, v[198:199]
	v_fmamk_f32 v32, v246, 0x3a800000, v175
	v_rsq_f32_e32 v32, v32
	s_nop 0
	v_pk_fma_f32 v[28:29], v[28:29], v[32:33], v[112:113] op_sel_hi:[1,0,1]
	v_pk_fma_f32 v[30:31], v[30:31], v[32:33], v[114:115] op_sel_hi:[1,0,1]
	v_pk_fma_f32 v[24:25], v[24:25], v[32:33], v[104:105] op_sel_hi:[1,0,1]
	v_pk_fma_f32 v[26:27], v[26:27], v[32:33], v[106:107] op_sel_hi:[1,0,1]
	v_pk_fma_f32 v[20:21], v[20:21], v[32:33], v[116:117] op_sel_hi:[1,0,1]
	v_pk_fma_f32 v[22:23], v[22:23], v[32:33], v[118:119] op_sel_hi:[1,0,1]
	v_pk_fma_f32 v[16:17], v[16:17], v[32:33], v[108:109] op_sel_hi:[1,0,1]
	v_pk_fma_f32 v[18:19], v[18:19], v[32:33], v[110:111] op_sel_hi:[1,0,1]
	v_pk_mul_f32 v[32:33], v[28:29], v[194:195]
	v_pk_mul_f32 v[36:37], v[30:31], v[194:195]
	v_pk_mul_f32 v[38:39], v[24:25], v[194:195]
	v_pk_mul_f32 v[40:41], v[26:27], v[194:195]
	v_exp_f32_e32 v32, v32
	v_exp_f32_e32 v33, v33
	v_exp_f32_e32 v36, v36
	v_exp_f32_e32 v37, v37
	v_exp_f32_e32 v38, v38
	v_exp_f32_e32 v39, v39
	v_exp_f32_e32 v40, v40
	v_exp_f32_e32 v41, v41
	v_pk_add_f32 v[32:33], v[32:33], v[196:197]
	v_pk_add_f32 v[36:37], v[36:37], v[196:197]
	v_pk_add_f32 v[38:39], v[38:39], v[196:197]
	v_pk_add_f32 v[40:41], v[40:41], v[196:197]
	v_rcp_f32_e32 v32, v32
	v_rcp_f32_e32 v33, v33
	v_rcp_f32_e32 v36, v36
	v_rcp_f32_e32 v37, v37
	v_rcp_f32_e32 v38, v38
	v_rcp_f32_e32 v39, v39
	v_rcp_f32_e32 v40, v40
	v_rcp_f32_e32 v41, v41
	v_pk_mul_f32 v[28:29], v[28:29], v[32:33]
	v_pk_mul_f32 v[30:31], v[30:31], v[36:37]
	v_pk_mul_f32 v[24:25], v[24:25], v[38:39]
	v_pk_mul_f32 v[26:27], v[26:27], v[40:41]
	v_pk_mul_f32 v[20:21], v[20:21], v[28:29]
	v_pk_mul_f32 v[22:23], v[22:23], v[30:31]
	v_pk_mul_f32 v[24:25], v[16:17], v[24:25]
	v_pk_mul_f32 v[26:27], v[18:19], v[26:27]
	v_cvt_pk_f16_f32 v16, v20, v21
	v_cvt_pk_f16_f32 v17, v22, v23
	v_cvt_pk_f16_f32 v18, v24, v25
	v_cvt_pk_f16_f32 v19, v26, v27
	global_store_dwordx4 v[34:35], v[16:19], off
	s_nop 0
	s_nop 0
	v_add_u32_e32 v17, 0xb0, v160
	v_lshl_add_u64 v[18:19], v[34:35], 0, v[198:199]
	v_fmamk_f32 v16, v247, 0x3a800000, v175
	v_rsq_f32_e32 v16, v16
	s_nop 0
	v_pk_fma_f32 v[12:13], v[12:13], v[16:17], v[112:113] op_sel_hi:[1,0,1]
	v_pk_fma_f32 v[14:15], v[14:15], v[16:17], v[114:115] op_sel_hi:[1,0,1]
	v_pk_fma_f32 v[8:9], v[8:9], v[16:17], v[104:105] op_sel_hi:[1,0,1]
	v_pk_fma_f32 v[10:11], v[10:11], v[16:17], v[106:107] op_sel_hi:[1,0,1]
	v_pk_fma_f32 v[4:5], v[4:5], v[16:17], v[116:117] op_sel_hi:[1,0,1]
	v_pk_fma_f32 v[6:7], v[6:7], v[16:17], v[118:119] op_sel_hi:[1,0,1]
	v_pk_fma_f32 v[0:1], v[0:1], v[16:17], v[108:109] op_sel_hi:[1,0,1]
	v_pk_fma_f32 v[2:3], v[2:3], v[16:17], v[110:111] op_sel_hi:[1,0,1]
	v_pk_mul_f32 v[16:17], v[12:13], v[194:195]
	v_pk_mul_f32 v[20:21], v[14:15], v[194:195]
	v_pk_mul_f32 v[22:23], v[8:9], v[194:195]
	v_pk_mul_f32 v[24:25], v[10:11], v[194:195]
	v_exp_f32_e32 v16, v16
	v_exp_f32_e32 v17, v17
	v_exp_f32_e32 v20, v20
	v_exp_f32_e32 v21, v21
	v_exp_f32_e32 v22, v22
	v_exp_f32_e32 v23, v23
	v_exp_f32_e32 v24, v24
	v_exp_f32_e32 v25, v25
	v_pk_add_f32 v[16:17], v[16:17], v[196:197]
	v_pk_add_f32 v[20:21], v[20:21], v[196:197]
	v_pk_add_f32 v[22:23], v[22:23], v[196:197]
	v_pk_add_f32 v[24:25], v[24:25], v[196:197]
	v_rcp_f32_e32 v16, v16
	v_rcp_f32_e32 v17, v17
	v_rcp_f32_e32 v20, v20
	v_rcp_f32_e32 v21, v21
	v_rcp_f32_e32 v22, v22
	v_rcp_f32_e32 v23, v23
	v_rcp_f32_e32 v24, v24
	v_rcp_f32_e32 v25, v25
	v_pk_mul_f32 v[12:13], v[12:13], v[16:17]
	v_pk_mul_f32 v[14:15], v[14:15], v[20:21]
	v_pk_mul_f32 v[8:9], v[8:9], v[22:23]
	v_pk_mul_f32 v[10:11], v[10:11], v[24:25]
	v_pk_mul_f32 v[4:5], v[4:5], v[12:13]
	v_pk_mul_f32 v[6:7], v[6:7], v[14:15]
	v_pk_mul_f32 v[8:9], v[0:1], v[8:9]
	v_pk_mul_f32 v[10:11], v[2:3], v[10:11]
	v_cvt_pk_f16_f32 v0, v4, v5
	v_cvt_pk_f16_f32 v1, v6, v7
	v_cvt_pk_f16_f32 v2, v8, v9
	v_cvt_pk_f16_f32 v3, v10, v11
	global_store_dwordx4 v[18:19], v[0:3], off
	s_cbranch_vccnz .LBB0_1581
	s_andn2_b64 vcc, exec, s[4:5]
	s_cbranch_vccnz .LBB0_1580
	s_barrier
	s_branch .LBB0_1580
